# P8 and P17 query GEMM k-loops: LDS fragment reads double-buffered per k-step (two register sets), next tile's first fragments read after the barrier
# baseline (speedup 1.0000x reference)
.LBB0_1920:
	s_or_b64 exec, exec, s[2:3]
	v_add_u32_e32 v2, s33, v194
	v_ashrrev_i32_e32 v3, 31, v2
	v_lshlrev_b64 v[2:3], 11, v[2:3]
	v_lshl_add_u64 v[168:169], s[82:83], 0, v[2:3]
	v_add_u32_e32 v2, s33, v195
	v_ashrrev_i32_e32 v3, 31, v2
	v_lshlrev_b64 v[2:3], 11, v[2:3]
	v_lshl_add_u64 v[172:173], s[82:83], 0, v[2:3]
	v_add_u32_e32 v2, s33, v196
	v_ashrrev_i32_e32 v3, 31, v2
	v_lshlrev_b64 v[2:3], 11, v[2:3]
	v_lshl_add_u64 v[176:177], s[82:83], 0, v[2:3]
	v_add_u32_e32 v2, s33, v1
	v_ashrrev_i32_e32 v3, 31, v2
	v_lshlrev_b64 v[2:3], 11, v[2:3]
	v_lshl_add_u64 v[166:167], s[82:83], 0, v[48:49]
	v_lshl_add_u64 v[170:171], s[82:83], 0, v[42:43]
	v_lshl_add_u64 v[174:175], s[82:83], 0, v[36:37]
	v_lshl_add_u64 v[178:179], s[82:83], 0, v[34:35]
	v_lshl_add_u64 v[180:181], s[82:83], 0, v[2:3]
	s_mov_b32 s35, 0
	v_mov_b32_e32 v51, v50
	v_mov_b32_e32 v52, v50
	v_mov_b32_e32 v53, v50
	v_mov_b32_e32 v54, v50
	v_mov_b32_e32 v55, v50
	v_mov_b32_e32 v56, v50
	v_mov_b32_e32 v57, v50
	v_mov_b32_e32 v58, v50
	v_mov_b32_e32 v59, v50
	v_mov_b32_e32 v60, v50
	v_mov_b32_e32 v61, v50
	v_mov_b32_e32 v62, v50
	v_mov_b32_e32 v63, v50
	v_mov_b32_e32 v64, v50
	v_mov_b32_e32 v65, v50
	v_mov_b32_e32 v34, v50
	v_mov_b32_e32 v35, v50
	v_mov_b32_e32 v36, v50
	v_mov_b32_e32 v37, v50
	v_mov_b32_e32 v38, v50
	v_mov_b32_e32 v39, v50
	v_mov_b32_e32 v40, v50
	v_mov_b32_e32 v41, v50
	v_mov_b32_e32 v42, v50
	v_mov_b32_e32 v43, v50
	v_mov_b32_e32 v44, v50
	v_mov_b32_e32 v45, v50
	v_mov_b32_e32 v46, v50
	v_mov_b32_e32 v47, v50
	v_mov_b32_e32 v48, v50
	v_mov_b32_e32 v49, v50
	v_mov_b32_e32 v18, v50
	v_mov_b32_e32 v19, v50
	v_mov_b32_e32 v20, v50
	v_mov_b32_e32 v21, v50
	v_mov_b32_e32 v22, v50
	v_mov_b32_e32 v23, v50
	v_mov_b32_e32 v24, v50
	v_mov_b32_e32 v25, v50
	v_mov_b32_e32 v26, v50
	v_mov_b32_e32 v27, v50
	v_mov_b32_e32 v28, v50
	v_mov_b32_e32 v29, v50
	v_mov_b32_e32 v30, v50
	v_mov_b32_e32 v31, v50
	v_mov_b32_e32 v32, v50
	v_mov_b32_e32 v33, v50
	v_mov_b32_e32 v2, v50
	v_mov_b32_e32 v3, v50
	v_mov_b32_e32 v4, v50
	v_mov_b32_e32 v5, v50
	v_mov_b32_e32 v6, v50
	v_mov_b32_e32 v7, v50
	v_mov_b32_e32 v8, v50
	v_mov_b32_e32 v9, v50
	v_mov_b32_e32 v10, v50
	v_mov_b32_e32 v11, v50
	v_mov_b32_e32 v12, v50
	v_mov_b32_e32 v13, v50
	v_mov_b32_e32 v14, v50
	v_mov_b32_e32 v15, v50
	v_mov_b32_e32 v16, v50
	v_mov_b32_e32 v17, v50
	s_waitcnt lgkmcnt(0)
	s_barrier
	ds_read_b128 v[206:209], v203 offset:0
	ds_read_b128 v[210:213], v204 offset:18432
	ds_read_b128 v[214:217], v204 offset:23040
	ds_read_b128 v[218:221], v203 offset:4608
	ds_read_b128 v[222:225], v203 offset:32
	ds_read_b128 v[226:229], v204 offset:18464
	ds_read_b128 v[230:233], v204 offset:23072
	ds_read_b128 v[234:237], v203 offset:4640
	s_branch .LBB0_1923

.LBB0_1922:
	s_add_i32 s35, s35, 2
	v_lshl_add_u64 v[166:167], v[166:167], 0, s[30:31]
	v_lshl_add_u64 v[168:169], v[168:169], 0, s[30:31]
	v_lshl_add_u64 v[170:171], v[170:171], 0, s[30:31]
	v_lshl_add_u64 v[172:173], v[172:173], 0, s[30:31]
	v_lshl_add_u64 v[174:175], v[174:175], 0, s[30:31]
	v_lshl_add_u64 v[176:177], v[176:177], 0, s[30:31]
	v_lshl_add_u64 v[178:179], v[178:179], 0, s[30:31]
	v_lshl_add_u64 v[180:181], v[180:181], 0, s[30:31]
	s_andn2_b64 vcc, exec, s[2:3]
	s_waitcnt lgkmcnt(4)
	v_mfma_f32_32x32x16_bf16 v[50:65], v[206:209], v[210:213], v[50:65]
	v_mfma_f32_32x32x16_bf16 v[34:49], v[206:209], v[214:217], v[34:49]
	v_mfma_f32_32x32x16_bf16 v[18:33], v[218:221], v[210:213], v[18:33]
	v_mfma_f32_32x32x16_bf16 v[2:17], v[218:221], v[214:217], v[2:17]
	ds_read_b128 v[206:209], v203 offset:36928
	ds_read_b128 v[210:213], v204 offset:55360
	ds_read_b128 v[214:217], v204 offset:59968
	ds_read_b128 v[218:221], v203 offset:41536
	s_waitcnt lgkmcnt(4)
	v_mfma_f32_32x32x16_bf16 v[50:65], v[222:225], v[226:229], v[50:65]
	v_mfma_f32_32x32x16_bf16 v[34:49], v[222:225], v[230:233], v[34:49]
	v_mfma_f32_32x32x16_bf16 v[18:33], v[234:237], v[226:229], v[18:33]
	v_mfma_f32_32x32x16_bf16 v[2:17], v[234:237], v[230:233], v[2:17]
	ds_read_b128 v[222:225], v203 offset:36960
	ds_read_b128 v[226:229], v204 offset:55392
	ds_read_b128 v[230:233], v204 offset:60000
	ds_read_b128 v[234:237], v203 offset:41568
	s_waitcnt lgkmcnt(4)
	v_mfma_f32_32x32x16_bf16 v[50:65], v[206:209], v[210:213], v[50:65]
	v_mfma_f32_32x32x16_bf16 v[34:49], v[206:209], v[214:217], v[34:49]
	s_waitcnt lgkmcnt(0)
	s_barrier
	v_mfma_f32_32x32x16_bf16 v[18:33], v[218:221], v[210:213], v[18:33]
	v_mfma_f32_32x32x16_bf16 v[2:17], v[218:221], v[214:217], v[2:17]
	ds_read_b128 v[206:209], v203 offset:0
	ds_read_b128 v[210:213], v204 offset:18432
	ds_read_b128 v[214:217], v204 offset:23040
	ds_read_b128 v[218:221], v203 offset:4608
	v_mfma_f32_32x32x16_bf16 v[50:65], v[222:225], v[226:229], v[50:65]
	v_mfma_f32_32x32x16_bf16 v[34:49], v[222:225], v[230:233], v[34:49]
	v_mfma_f32_32x32x16_bf16 v[18:33], v[234:237], v[226:229], v[18:33]
	v_mfma_f32_32x32x16_bf16 v[2:17], v[234:237], v[230:233], v[2:17]
	ds_read_b128 v[222:225], v203 offset:32
	ds_read_b128 v[226:229], v204 offset:18464
	ds_read_b128 v[230:233], v204 offset:23072
	ds_read_b128 v[234:237], v203 offset:4640
	s_cbranch_vccz .LBB0_1943

.LBB0_1933:
	s_cmp_gt_u32 s35, 13
	s_cselect_b64 s[2:3], -1, 0
	s_and_b64 vcc, exec, s[2:3]
	s_waitcnt lgkmcnt(4)
	v_mfma_f32_32x32x16_bf16 v[50:65], v[206:209], v[210:213], v[50:65]
	v_mfma_f32_32x32x16_bf16 v[34:49], v[206:209], v[214:217], v[34:49]
	v_mfma_f32_32x32x16_bf16 v[18:33], v[218:221], v[210:213], v[18:33]
	v_mfma_f32_32x32x16_bf16 v[2:17], v[218:221], v[214:217], v[2:17]
	ds_read_b128 v[206:209], v203 offset:64
	ds_read_b128 v[210:213], v204 offset:18496
	ds_read_b128 v[214:217], v204 offset:23104
	ds_read_b128 v[218:221], v203 offset:4672
	s_waitcnt lgkmcnt(4)
	v_mfma_f32_32x32x16_bf16 v[50:65], v[222:225], v[226:229], v[50:65]
	v_mfma_f32_32x32x16_bf16 v[34:49], v[222:225], v[230:233], v[34:49]
	v_mfma_f32_32x32x16_bf16 v[18:33], v[234:237], v[226:229], v[18:33]
	v_mfma_f32_32x32x16_bf16 v[2:17], v[234:237], v[230:233], v[2:17]
	ds_read_b128 v[222:225], v203 offset:96
	ds_read_b128 v[226:229], v204 offset:18528
	ds_read_b128 v[230:233], v204 offset:23136
	ds_read_b128 v[234:237], v203 offset:4704
	s_waitcnt lgkmcnt(4)
	v_mfma_f32_32x32x16_bf16 v[50:65], v[206:209], v[210:213], v[50:65]
	v_mfma_f32_32x32x16_bf16 v[34:49], v[206:209], v[214:217], v[34:49]
	s_waitcnt lgkmcnt(0)
	s_barrier
	v_mfma_f32_32x32x16_bf16 v[18:33], v[218:221], v[210:213], v[18:33]
	v_mfma_f32_32x32x16_bf16 v[2:17], v[218:221], v[214:217], v[2:17]
	ds_read_b128 v[206:209], v203 offset:36864
	ds_read_b128 v[210:213], v204 offset:55296
	ds_read_b128 v[214:217], v204 offset:59904
	ds_read_b128 v[218:221], v203 offset:41472
	v_mfma_f32_32x32x16_bf16 v[50:65], v[222:225], v[226:229], v[50:65]
	v_mfma_f32_32x32x16_bf16 v[34:49], v[222:225], v[230:233], v[34:49]
	v_mfma_f32_32x32x16_bf16 v[18:33], v[234:237], v[226:229], v[18:33]
	v_mfma_f32_32x32x16_bf16 v[2:17], v[234:237], v[230:233], v[2:17]
	ds_read_b128 v[222:225], v203 offset:36896
	ds_read_b128 v[226:229], v204 offset:55328
	ds_read_b128 v[230:233], v204 offset:59936
	ds_read_b128 v[234:237], v203 offset:41504
	s_cbranch_vccnz .LBB0_1922
	s_cmp_gt_u32 s35, 11
	s_waitcnt vmcnt(3)
	ds_write_b128 v137, v[86:89]
	ds_write_b128 v137, v[94:97] offset:18432
	s_waitcnt vmcnt(2)
	ds_write_b128 v137, v[110:113] offset:4608
	ds_write_b128 v137, v[98:101] offset:23040
	s_waitcnt vmcnt(1)
	ds_write_b128 v137, v[114:117] offset:9216
	ds_write_b128 v137, v[118:121] offset:27648
	s_waitcnt vmcnt(0)
	ds_write_b128 v137, v[122:125] offset:13824
	ds_write_b128 v137, v[126:129] offset:32256
	s_cbranch_scc1 .LBB0_1922
	v_lshl_add_u64 v[86:87], v[180:181], 0, v[138:139]
	v_add_co_u32_e32 v86, vcc, 0xc4c0000, v86
	v_mov_b32_e32 v100, 0
	s_nop 0
	v_addc_co_u32_e32 v87, vcc, 0, v87, vcc
	global_load_dwordx4 v[86:89], v[86:87], off offset:512
	v_mov_b32_e32 v101, v130
	v_mov_b64_e32 v[96:97], v[100:101]
	v_mov_b64_e32 v[94:95], v[100:101]
	s_and_saveexec_b64 s[36:37], s[12:13]
	s_cbranch_execz .LBB0_1937
	v_lshl_add_u64 v[94:95], v[178:179], 0, v[138:139]
	v_add_co_u32_e32 v94, vcc, 0x99d0000, v94
	s_nop 1
	v_addc_co_u32_e32 v95, vcc, 0, v95, vcc
	global_load_dwordx4 v[94:97], v[94:95], off offset:512

.LBB0_1943:
	s_waitcnt lgkmcnt(0)
	s_nop 7
	v_cvt_pk_bf16_f32 v50, v50, s0
	s_barrier
	ds_write_b16 v197, v50
	v_cvt_pk_bf16_f32 v50, v51, s0
	ds_write_b16 v197, v50 offset:272
	v_cvt_pk_bf16_f32 v50, v52, s0
	ds_write_b16 v197, v50 offset:544
	v_cvt_pk_bf16_f32 v50, v53, s0
	ds_write_b16 v197, v50 offset:816
	v_cvt_pk_bf16_f32 v50, v54, s0
	ds_write_b16 v197, v50 offset:2176
	v_cvt_pk_bf16_f32 v50, v55, s0
	ds_write_b16 v197, v50 offset:2448
	v_cvt_pk_bf16_f32 v50, v56, s0
	v_cvt_pk_bf16_f32 v34, v34, s0
	ds_write_b16 v197, v50 offset:2720
	v_cvt_pk_bf16_f32 v50, v57, s0
	ds_write_b16 v197, v34 offset:64
	v_cvt_pk_bf16_f32 v34, v35, s0
	ds_write_b16 v197, v50 offset:2992
	v_cvt_pk_bf16_f32 v50, v58, s0
	ds_write_b16 v197, v34 offset:336
	v_cvt_pk_bf16_f32 v34, v36, s0
	ds_write_b16 v197, v50 offset:4352
	v_cvt_pk_bf16_f32 v50, v59, s0
	ds_write_b16 v197, v34 offset:608
	v_cvt_pk_bf16_f32 v34, v37, s0
	s_lshl_b32 s3, s34, 3
	ds_write_b16 v197, v50 offset:4624
	v_cvt_pk_bf16_f32 v50, v60, s0
	ds_write_b16 v197, v34 offset:880
	v_cvt_pk_bf16_f32 v34, v38, s0
	s_ashr_i32 s2, s34, 1
	s_and_b32 s3, s3, 8
	ds_write_b16 v197, v50 offset:4896
	v_cvt_pk_bf16_f32 v50, v61, s0
	ds_write_b16 v197, v34 offset:2240
	v_cvt_pk_bf16_f32 v34, v39, s0
	s_add_i32 s2, s3, s2
	ds_write_b16 v197, v50 offset:5168
	v_cvt_pk_bf16_f32 v50, v62, s0
	ds_write_b16 v197, v34 offset:2512
	v_cvt_pk_bf16_f32 v34, v40, s0
	s_ashr_i32 s3, s2, 31
	ds_write_b16 v197, v50 offset:6528
	v_cvt_pk_bf16_f32 v50, v63, s0
	ds_write_b16 v197, v34 offset:2784
	v_cvt_pk_bf16_f32 v34, v41, s0
	s_lshl_b64 s[2:3], s[2:3], 15
	ds_write_b16 v197, v50 offset:6800
	v_cvt_pk_bf16_f32 v50, v64, s0
	ds_write_b16 v197, v34 offset:3056
	v_cvt_pk_bf16_f32 v34, v42, s0
	s_add_u32 s2, s42, s2
	ds_write_b16 v197, v50 offset:7072
	v_cvt_pk_bf16_f32 v50, v65, s0
	ds_write_b16 v197, v34 offset:4416
	v_cvt_pk_bf16_f32 v34, v43, s0
	s_addc_u32 s3, s43, s3
	v_mov_b32_e32 v141, v130
	v_mov_b32_e32 v143, v130
	v_mov_b32_e32 v147, v130
	v_mov_b32_e32 v151, v130
	ds_write_b16 v197, v50 offset:7344
	ds_write_b16 v197, v34 offset:4688
	v_lshl_add_u64 v[36:37], s[2:3], 0, v[140:141]
	v_lshlrev_b32_e32 v34, 1, v136
	v_mov_b32_e32 v35, v130
	v_lshl_add_u64 v[38:39], s[2:3], 0, v[142:143]
	v_mov_b32_e32 v145, v130
	v_lshl_add_u64 v[50:51], s[2:3], 0, v[146:147]
	v_mov_b32_e32 v149, v130
	v_lshl_add_u64 v[52:53], s[2:3], 0, v[150:151]
	v_mov_b32_e32 v153, v130
	v_lshl_add_u64 v[36:37], v[36:37], 0, v[34:35]
	v_lshl_add_u64 v[40:41], v[38:39], 0, v[144:145]
	v_lshl_add_u64 v[50:51], v[50:51], 0, v[148:149]
	v_lshl_add_u64 v[54:55], v[52:53], 0, v[152:153]
	global_load_dwordx4 v[36:39], v[36:37], off
	s_nop 0
	global_load_dwordx4 v[40:43], v[40:41], off
	s_nop 0
	global_load_dwordx4 v[50:53], v[50:51], off
	s_nop 0
	global_load_dwordx4 v[54:57], v[54:55], off
	v_mov_b32_e32 v155, v130
	v_lshl_add_u64 v[58:59], s[2:3], 0, v[154:155]
	v_lshl_add_u64 v[58:59], v[58:59], 0, v[34:35]
	global_load_dwordx4 v[58:61], v[58:59], off
	v_cvt_pk_bf16_f32 v35, v45, s0
	ds_write_b16 v197, v35 offset:5232
	v_cvt_pk_bf16_f32 v35, v46, s0
	ds_write_b16 v197, v35 offset:6592
	v_cvt_pk_bf16_f32 v35, v47, s0
	ds_write_b16 v197, v35 offset:6864
	v_cvt_pk_bf16_f32 v35, v48, s0
	v_cvt_pk_bf16_f32 v44, v44, s0
	ds_write_b16 v197, v35 offset:7136
	v_cvt_pk_bf16_f32 v35, v49, s0
	v_cvt_pk_bf16_f32 v18, v18, s0
	v_cvt_pk_bf16_f32 v2, v2, s0
	ds_write_b16 v197, v44 offset:4960
	ds_write_b16 v197, v35 offset:7408
	ds_write_b16 v198, v18
	v_cvt_pk_bf16_f32 v18, v19, s0
	ds_write_b16 v198, v2 offset:64
	v_cvt_pk_bf16_f32 v2, v3, s0
	ds_write_b16 v198, v18 offset:272
	v_cvt_pk_bf16_f32 v18, v20, s0
	ds_write_b16 v198, v2 offset:336
	v_cvt_pk_bf16_f32 v2, v4, s0
	ds_write_b16 v198, v18 offset:544
	v_cvt_pk_bf16_f32 v18, v21, s0
	ds_write_b16 v198, v2 offset:608
	v_cvt_pk_bf16_f32 v2, v5, s0
	ds_write_b16 v198, v18 offset:816
	v_cvt_pk_bf16_f32 v18, v22, s0
	ds_write_b16 v198, v2 offset:880
	v_cvt_pk_bf16_f32 v2, v6, s0
	ds_write_b16 v198, v18 offset:2176
	v_cvt_pk_bf16_f32 v18, v23, s0
	ds_write_b16 v198, v2 offset:2240
	v_cvt_pk_bf16_f32 v2, v7, s0
	ds_write_b16 v198, v18 offset:2448
	v_cvt_pk_bf16_f32 v18, v24, s0
	ds_write_b16 v198, v2 offset:2512
	v_cvt_pk_bf16_f32 v2, v8, s0
	ds_write_b16 v198, v18 offset:2720
	v_cvt_pk_bf16_f32 v18, v25, s0
	ds_write_b16 v198, v2 offset:2784
	v_cvt_pk_bf16_f32 v2, v9, s0
	ds_write_b16 v198, v18 offset:2992
	v_cvt_pk_bf16_f32 v18, v26, s0
	ds_write_b16 v198, v2 offset:3056
	v_cvt_pk_bf16_f32 v2, v10, s0
	ds_write_b16 v198, v18 offset:4352
	v_cvt_pk_bf16_f32 v18, v27, s0
	ds_write_b16 v198, v2 offset:4416
	v_cvt_pk_bf16_f32 v2, v11, s0
	ds_write_b16 v198, v18 offset:4624
	v_cvt_pk_bf16_f32 v18, v28, s0
	ds_write_b16 v198, v2 offset:4688
	v_cvt_pk_bf16_f32 v2, v12, s0
	ds_write_b16 v198, v18 offset:4896
	v_cvt_pk_bf16_f32 v18, v29, s0
	ds_write_b16 v198, v2 offset:4960
	v_cvt_pk_bf16_f32 v2, v13, s0
	ds_write_b16 v198, v18 offset:5168
	v_cvt_pk_bf16_f32 v18, v30, s0
	ds_write_b16 v198, v2 offset:5232
	v_cvt_pk_bf16_f32 v2, v14, s0
	ds_write_b16 v198, v18 offset:6528
	v_cvt_pk_bf16_f32 v18, v31, s0
	ds_write_b16 v198, v2 offset:6592
	v_cvt_pk_bf16_f32 v2, v15, s0
	ds_write_b16 v198, v18 offset:6800
	v_cvt_pk_bf16_f32 v18, v32, s0
	ds_write_b16 v198, v2 offset:6864
	v_cvt_pk_bf16_f32 v2, v16, s0
	ds_write_b16 v198, v18 offset:7072
	v_cvt_pk_bf16_f32 v18, v33, s0
	ds_write_b16 v198, v2 offset:7136
	v_cvt_pk_bf16_f32 v2, v17, s0
	ds_write_b16 v198, v18 offset:7344
	ds_write_b16 v198, v2 offset:7408
	s_waitcnt vmcnt(4)
	ds_write_b128 v186, v[36:39]
	s_waitcnt vmcnt(3)
	ds_write_b128 v187, v[40:43]
	s_waitcnt vmcnt(2)
	ds_write_b128 v188, v[50:53]
	s_waitcnt vmcnt(1)
	ds_write_b128 v189, v[54:57]
	s_waitcnt vmcnt(0)
	ds_write_b128 v190, v[58:61]
	s_and_saveexec_b64 s[12:13], s[4:5]
	s_cbranch_execz .LBB0_1947
	v_mov_b32_e32 v157, v130
	v_lshl_add_u64 v[2:3], s[2:3], 0, v[156:157]
	v_mov_b32_e32 v159, v130
	v_lshl_add_u64 v[2:3], v[2:3], 0, v[158:159]
	global_load_dwordx4 v[2:5], v[2:3], off
	s_waitcnt vmcnt(0)
	ds_write_b128 v191, v[2:5]
	s_and_saveexec_b64 s[14:15], s[6:7]
	s_xor_b64 s[14:15], exec, s[14:15]
	s_cbranch_execz .LBB0_1947
	v_mov_b32_e32 v161, v130
	v_lshl_add_u64 v[2:3], s[2:3], 0, v[160:161]
	v_mov_b32_e32 v35, v130
	v_lshl_add_u64 v[2:3], v[2:3], 0, v[34:35]
	global_load_dwordx4 v[2:5], v[2:3], off
	s_waitcnt vmcnt(0)
	ds_write_b128 v192, v[2:5]
	s_and_saveexec_b64 s[14:15], s[8:9]
	s_xor_b64 s[14:15], exec, s[14:15]
	s_cbranch_execz .LBB0_1947
	v_mov_b32_e32 v163, v130
	v_lshl_add_u64 v[2:3], s[2:3], 0, v[162:163]
	v_mov_b32_e32 v165, v130
	v_lshl_add_u64 v[2:3], v[2:3], 0, v[164:165]
	global_load_dwordx4 v[2:5], v[2:3], off
	s_waitcnt vmcnt(0)
	ds_write_b128 v193, v[2:5]

.LBB0_3134:
	s_cmp_gt_u32 s35, 13
	s_cselect_b64 s[2:3], -1, 0
	s_and_b64 vcc, exec, s[2:3]
	s_waitcnt lgkmcnt(4)
	v_mfma_f32_32x32x16_bf16 v[50:65], v[206:209], v[210:213], v[50:65]
	v_mfma_f32_32x32x16_bf16 v[34:49], v[206:209], v[214:217], v[34:49]
	v_mfma_f32_32x32x16_bf16 v[18:33], v[218:221], v[210:213], v[18:33]
	v_mfma_f32_32x32x16_bf16 v[2:17], v[218:221], v[214:217], v[2:17]
	ds_read_b128 v[206:209], v203 offset:64
	ds_read_b128 v[210:213], v204 offset:18496
	ds_read_b128 v[214:217], v204 offset:23104
	ds_read_b128 v[218:221], v203 offset:4672
	s_waitcnt lgkmcnt(4)
	v_mfma_f32_32x32x16_bf16 v[50:65], v[222:225], v[226:229], v[50:65]
	v_mfma_f32_32x32x16_bf16 v[34:49], v[222:225], v[230:233], v[34:49]
	v_mfma_f32_32x32x16_bf16 v[18:33], v[234:237], v[226:229], v[18:33]
	v_mfma_f32_32x32x16_bf16 v[2:17], v[234:237], v[230:233], v[2:17]
	ds_read_b128 v[222:225], v203 offset:96
	ds_read_b128 v[226:229], v204 offset:18528
	ds_read_b128 v[230:233], v204 offset:23136
	ds_read_b128 v[234:237], v203 offset:4704
	s_waitcnt lgkmcnt(4)
	v_mfma_f32_32x32x16_bf16 v[50:65], v[206:209], v[210:213], v[50:65]
	v_mfma_f32_32x32x16_bf16 v[34:49], v[206:209], v[214:217], v[34:49]
	s_waitcnt lgkmcnt(0)
	s_barrier
	v_mfma_f32_32x32x16_bf16 v[18:33], v[218:221], v[210:213], v[18:33]
	v_mfma_f32_32x32x16_bf16 v[2:17], v[218:221], v[214:217], v[2:17]
	ds_read_b128 v[206:209], v203 offset:36864
	ds_read_b128 v[210:213], v204 offset:55296
	ds_read_b128 v[214:217], v204 offset:59904
	ds_read_b128 v[218:221], v203 offset:41472
	v_mfma_f32_32x32x16_bf16 v[50:65], v[222:225], v[226:229], v[50:65]
	v_mfma_f32_32x32x16_bf16 v[34:49], v[222:225], v[230:233], v[34:49]
	v_mfma_f32_32x32x16_bf16 v[18:33], v[234:237], v[226:229], v[18:33]
	v_mfma_f32_32x32x16_bf16 v[2:17], v[234:237], v[230:233], v[2:17]
	ds_read_b128 v[222:225], v203 offset:36896
	ds_read_b128 v[226:229], v204 offset:55328
	ds_read_b128 v[230:233], v204 offset:59936
	ds_read_b128 v[234:237], v203 offset:41504
	s_cbranch_vccnz .LBB0_3123
	s_cmp_gt_u32 s35, 11
	s_waitcnt vmcnt(3)
	ds_write_b128 v137, v[86:89]
	ds_write_b128 v137, v[94:97] offset:18432
	s_waitcnt vmcnt(2)
	ds_write_b128 v137, v[110:113] offset:4608
	ds_write_b128 v137, v[98:101] offset:23040
	s_waitcnt vmcnt(1)
	ds_write_b128 v137, v[114:117] offset:9216
	ds_write_b128 v137, v[118:121] offset:27648
	s_waitcnt vmcnt(0)
	ds_write_b128 v137, v[122:125] offset:13824
	ds_write_b128 v137, v[126:129] offset:32256
	s_cbranch_scc1 .LBB0_3123
	v_lshl_add_u64 v[86:87], v[180:181], 0, v[138:139]
	v_add_co_u32_e32 v86, vcc, 0x149c0000, v86
	v_mov_b32_e32 v100, 0
	s_nop 0
	v_addc_co_u32_e32 v87, vcc, 0, v87, vcc
	global_load_dwordx4 v[86:89], v[86:87], off offset:512
	v_mov_b32_e32 v101, v130
	v_mov_b64_e32 v[96:97], v[100:101]
	v_mov_b64_e32 v[94:95], v[100:101]
	s_and_saveexec_b64 s[36:37], s[12:13]
	s_cbranch_execz .LBB0_3138
	v_lshl_add_u64 v[94:95], v[178:179], 0, v[138:139]
	v_add_co_u32_e32 v94, vcc, 0x9dd0000, v94
	s_nop 1
	v_addc_co_u32_e32 v95, vcc, 0, v95, vcc
	global_load_dwordx4 v[94:97], v[94:95], off offset:512

.LBB0_3144:
	s_waitcnt lgkmcnt(0)
	s_nop 7
	v_cvt_pk_bf16_f32 v50, v50, s0
	s_barrier
	ds_write_b16 v197, v50
	v_cvt_pk_bf16_f32 v50, v51, s0
	ds_write_b16 v197, v50 offset:272
	v_cvt_pk_bf16_f32 v50, v52, s0
	ds_write_b16 v197, v50 offset:544
	v_cvt_pk_bf16_f32 v50, v53, s0
	ds_write_b16 v197, v50 offset:816
	v_cvt_pk_bf16_f32 v50, v54, s0
	ds_write_b16 v197, v50 offset:2176
	v_cvt_pk_bf16_f32 v50, v55, s0
	ds_write_b16 v197, v50 offset:2448
	v_cvt_pk_bf16_f32 v50, v56, s0
	v_cvt_pk_bf16_f32 v34, v34, s0
	ds_write_b16 v197, v50 offset:2720
	v_cvt_pk_bf16_f32 v50, v57, s0
	ds_write_b16 v197, v34 offset:64
	v_cvt_pk_bf16_f32 v34, v35, s0
	ds_write_b16 v197, v50 offset:2992
	v_cvt_pk_bf16_f32 v50, v58, s0
	ds_write_b16 v197, v34 offset:336
	v_cvt_pk_bf16_f32 v34, v36, s0
	s_lshl_b32 s3, s34, 3
	ds_write_b16 v197, v50 offset:4352
	v_cvt_pk_bf16_f32 v50, v59, s0
	ds_write_b16 v197, v34 offset:608
	v_cvt_pk_bf16_f32 v34, v37, s0
	s_ashr_i32 s2, s34, 1
	s_and_b32 s3, s3, 8
	ds_write_b16 v197, v50 offset:4624
	v_cvt_pk_bf16_f32 v50, v60, s0
	ds_write_b16 v197, v34 offset:880
	v_cvt_pk_bf16_f32 v34, v38, s0
	s_add_i32 s2, s2, s3
	ds_write_b16 v197, v50 offset:4896
	v_cvt_pk_bf16_f32 v50, v61, s0
	ds_write_b16 v197, v34 offset:2240
	v_cvt_pk_bf16_f32 v34, v39, s0
	s_add_i32 s2, s2, 16
	ds_write_b16 v197, v50 offset:5168
	v_cvt_pk_bf16_f32 v50, v62, s0
	ds_write_b16 v197, v34 offset:2512
	v_cvt_pk_bf16_f32 v34, v40, s0
	s_ashr_i32 s3, s2, 31
	ds_write_b16 v197, v50 offset:6528
	v_cvt_pk_bf16_f32 v50, v63, s0
	ds_write_b16 v197, v34 offset:2784
	v_cvt_pk_bf16_f32 v34, v41, s0
	s_lshl_b64 s[2:3], s[2:3], 15
	ds_write_b16 v197, v50 offset:6800
	v_cvt_pk_bf16_f32 v50, v64, s0
	ds_write_b16 v197, v34 offset:3056
	v_cvt_pk_bf16_f32 v34, v42, s0
	s_add_u32 s2, s42, s2
	ds_write_b16 v197, v50 offset:7072
	v_cvt_pk_bf16_f32 v50, v65, s0
	ds_write_b16 v197, v34 offset:4416
	v_cvt_pk_bf16_f32 v34, v43, s0
	s_addc_u32 s3, s43, s3
	v_mov_b32_e32 v141, v130
	v_mov_b32_e32 v143, v130
	v_mov_b32_e32 v147, v130
	v_mov_b32_e32 v151, v130
	ds_write_b16 v197, v50 offset:7344
	ds_write_b16 v197, v34 offset:4688
	v_lshl_add_u64 v[36:37], s[2:3], 0, v[140:141]
	v_lshlrev_b32_e32 v34, 1, v136
	v_mov_b32_e32 v35, v130
	v_lshl_add_u64 v[38:39], s[2:3], 0, v[142:143]
	v_mov_b32_e32 v145, v130
	v_lshl_add_u64 v[50:51], s[2:3], 0, v[146:147]
	v_mov_b32_e32 v149, v130
	v_lshl_add_u64 v[52:53], s[2:3], 0, v[150:151]
	v_mov_b32_e32 v153, v130
	v_lshl_add_u64 v[36:37], v[36:37], 0, v[34:35]
	v_lshl_add_u64 v[40:41], v[38:39], 0, v[144:145]
	v_lshl_add_u64 v[50:51], v[50:51], 0, v[148:149]
	v_lshl_add_u64 v[54:55], v[52:53], 0, v[152:153]
	global_load_dwordx4 v[36:39], v[36:37], off
	s_nop 0
	global_load_dwordx4 v[40:43], v[40:41], off
	s_nop 0
	global_load_dwordx4 v[50:53], v[50:51], off
	s_nop 0
	global_load_dwordx4 v[54:57], v[54:55], off
	v_mov_b32_e32 v155, v130
	v_lshl_add_u64 v[58:59], s[2:3], 0, v[154:155]
	v_lshl_add_u64 v[58:59], v[58:59], 0, v[34:35]
	global_load_dwordx4 v[58:61], v[58:59], off
	v_cvt_pk_bf16_f32 v35, v45, s0
	ds_write_b16 v197, v35 offset:5232
	v_cvt_pk_bf16_f32 v35, v46, s0
	ds_write_b16 v197, v35 offset:6592
	v_cvt_pk_bf16_f32 v35, v47, s0
	ds_write_b16 v197, v35 offset:6864
	v_cvt_pk_bf16_f32 v35, v48, s0
	v_cvt_pk_bf16_f32 v44, v44, s0
	ds_write_b16 v197, v35 offset:7136
	v_cvt_pk_bf16_f32 v35, v49, s0
	v_cvt_pk_bf16_f32 v18, v18, s0
	v_cvt_pk_bf16_f32 v2, v2, s0
	ds_write_b16 v197, v44 offset:4960
	ds_write_b16 v197, v35 offset:7408
	ds_write_b16 v198, v18
	v_cvt_pk_bf16_f32 v18, v19, s0
	ds_write_b16 v198, v2 offset:64
	v_cvt_pk_bf16_f32 v2, v3, s0
	ds_write_b16 v198, v18 offset:272
	v_cvt_pk_bf16_f32 v18, v20, s0
	ds_write_b16 v198, v2 offset:336
	v_cvt_pk_bf16_f32 v2, v4, s0
	ds_write_b16 v198, v18 offset:544
	v_cvt_pk_bf16_f32 v18, v21, s0
	ds_write_b16 v198, v2 offset:608
	v_cvt_pk_bf16_f32 v2, v5, s0
	ds_write_b16 v198, v18 offset:816
	v_cvt_pk_bf16_f32 v18, v22, s0
	ds_write_b16 v198, v2 offset:880
	v_cvt_pk_bf16_f32 v2, v6, s0
	ds_write_b16 v198, v18 offset:2176
	v_cvt_pk_bf16_f32 v18, v23, s0
	ds_write_b16 v198, v2 offset:2240
	v_cvt_pk_bf16_f32 v2, v7, s0
	ds_write_b16 v198, v18 offset:2448
	v_cvt_pk_bf16_f32 v18, v24, s0
	ds_write_b16 v198, v2 offset:2512
	v_cvt_pk_bf16_f32 v2, v8, s0
	ds_write_b16 v198, v18 offset:2720
	v_cvt_pk_bf16_f32 v18, v25, s0
	ds_write_b16 v198, v2 offset:2784
	v_cvt_pk_bf16_f32 v2, v9, s0
	ds_write_b16 v198, v18 offset:2992
	v_cvt_pk_bf16_f32 v18, v26, s0
	ds_write_b16 v198, v2 offset:3056
	v_cvt_pk_bf16_f32 v2, v10, s0
	ds_write_b16 v198, v18 offset:4352
	v_cvt_pk_bf16_f32 v18, v27, s0
	ds_write_b16 v198, v2 offset:4416
	v_cvt_pk_bf16_f32 v2, v11, s0
	ds_write_b16 v198, v18 offset:4624
	v_cvt_pk_bf16_f32 v18, v28, s0
	ds_write_b16 v198, v2 offset:4688
	v_cvt_pk_bf16_f32 v2, v12, s0
	ds_write_b16 v198, v18 offset:4896
	v_cvt_pk_bf16_f32 v18, v29, s0
	ds_write_b16 v198, v2 offset:4960
	v_cvt_pk_bf16_f32 v2, v13, s0
	ds_write_b16 v198, v18 offset:5168
	v_cvt_pk_bf16_f32 v18, v30, s0
	ds_write_b16 v198, v2 offset:5232
	v_cvt_pk_bf16_f32 v2, v14, s0
	ds_write_b16 v198, v18 offset:6528
	v_cvt_pk_bf16_f32 v18, v31, s0
	ds_write_b16 v198, v2 offset:6592
	v_cvt_pk_bf16_f32 v2, v15, s0
	ds_write_b16 v198, v18 offset:6800
	v_cvt_pk_bf16_f32 v18, v32, s0
	ds_write_b16 v198, v2 offset:6864
	v_cvt_pk_bf16_f32 v2, v16, s0
	ds_write_b16 v198, v18 offset:7072
	v_cvt_pk_bf16_f32 v18, v33, s0
	ds_write_b16 v198, v2 offset:7136
	v_cvt_pk_bf16_f32 v2, v17, s0
	ds_write_b16 v198, v18 offset:7344
	ds_write_b16 v198, v2 offset:7408
	s_waitcnt vmcnt(4)
	ds_write_b128 v186, v[36:39]
	s_waitcnt vmcnt(3)
	ds_write_b128 v187, v[40:43]
	s_waitcnt vmcnt(2)
	ds_write_b128 v188, v[50:53]
	s_waitcnt vmcnt(1)
	ds_write_b128 v189, v[54:57]
	s_waitcnt vmcnt(0)
	ds_write_b128 v190, v[58:61]
	s_and_saveexec_b64 s[12:13], s[4:5]
	s_cbranch_execz .LBB0_3148
	v_mov_b32_e32 v157, v130
	v_lshl_add_u64 v[2:3], s[2:3], 0, v[156:157]
	v_mov_b32_e32 v159, v130
	v_lshl_add_u64 v[2:3], v[2:3], 0, v[158:159]
	global_load_dwordx4 v[2:5], v[2:3], off
	s_waitcnt vmcnt(0)
	ds_write_b128 v191, v[2:5]
	s_and_saveexec_b64 s[14:15], s[6:7]
	s_xor_b64 s[14:15], exec, s[14:15]
	s_cbranch_execz .LBB0_3148
	v_mov_b32_e32 v161, v130
	v_lshl_add_u64 v[2:3], s[2:3], 0, v[160:161]
	v_mov_b32_e32 v35, v130
	v_lshl_add_u64 v[2:3], v[2:3], 0, v[34:35]
	global_load_dwordx4 v[2:5], v[2:3], off
	s_waitcnt vmcnt(0)
	ds_write_b128 v192, v[2:5]
	s_and_saveexec_b64 s[14:15], s[8:9]
	s_xor_b64 s[14:15], exec, s[14:15]
	s_cbranch_execz .LBB0_3148
	v_mov_b32_e32 v163, v130
	v_lshl_add_u64 v[2:3], s[2:3], 0, v[162:163]
	v_mov_b32_e32 v165, v130
	v_lshl_add_u64 v[2:3], v[2:3], 0, v[164:165]
	global_load_dwordx4 v[2:5], v[2:3], off
	s_waitcnt vmcnt(0)
	ds_write_b128 v193, v[2:5]
